# E21: P4 epilogue per-channel scales staged by LDS-DMA at the unit-loop head; the four serial global loads in the epilogue become ds_read_b128
# speedup vs baseline: 1.0229x; 1.0043x over previous
.LBB0_799:
	s_ashr_i32 s75, s74, 31
	s_lshl_b64 s[10:11], s[74:75], 20
	v_readlane_b32 s12, v250, 4
	v_readlane_b32 s13, v250, 5
	s_add_u32 s76, s12, s10
	s_addc_u32 s77, s13, s11
	s_and_b64 s[10:11], s[2:3], exec
	s_cselect_b32 s5, s77, s9
	s_cselect_b32 s10, s76, s8
	s_ashr_i32 s73, s72, 31
	s_lshl_b64 s[78:79], s[72:73], 20
	v_readlane_b32 s12, v251, 54
	v_readlane_b32 s13, v251, 55
	s_add_u32 s84, s12, s78
	s_addc_u32 s85, s13, s79
	s_and_b64 s[78:79], s[2:3], exec
	s_cselect_b32 s11, s85, s7
	s_cselect_b32 s73, s84, s6
	s_add_u32 s75, s6, 0x100
	s_addc_u32 s78, s7, 0
	s_add_u32 s6, s8, 0x80080
	v_mov_b32_e32 v68, 0
	s_addc_u32 s7, s9, 0
	s_mov_b32 s8, -2
	v_mov_b32_e32 v69, v68
	v_mov_b32_e32 v70, v68
	v_mov_b32_e32 v71, v68
	v_mov_b32_e32 v60, v68
	v_mov_b32_e32 v61, v68
	v_mov_b32_e32 v62, v68
	v_mov_b32_e32 v63, v68
	v_mov_b32_e32 v36, v68
	v_mov_b32_e32 v37, v68
	v_mov_b32_e32 v38, v68
	v_mov_b32_e32 v39, v68
	v_mov_b32_e32 v76, v68
	v_mov_b32_e32 v77, v68
	v_mov_b32_e32 v78, v68
	v_mov_b32_e32 v79, v68
	v_mov_b32_e32 v32, v68
	v_mov_b32_e32 v33, v68
	v_mov_b32_e32 v34, v68
	v_mov_b32_e32 v35, v68
	v_mov_b32_e32 v100, v68
	v_mov_b32_e32 v101, v68
	v_mov_b32_e32 v102, v68
	v_mov_b32_e32 v103, v68
	v_mov_b32_e32 v40, v68
	v_mov_b32_e32 v41, v68
	v_mov_b32_e32 v42, v68
	v_mov_b32_e32 v43, v68
	v_mov_b32_e32 v104, v68
	v_mov_b32_e32 v105, v68
	v_mov_b32_e32 v106, v68
	v_mov_b32_e32 v107, v68
	v_mov_b32_e32 v44, v68
	v_mov_b32_e32 v45, v68
	v_mov_b32_e32 v46, v68
	v_mov_b32_e32 v47, v68
	v_mov_b32_e32 v108, v68
	v_mov_b32_e32 v109, v68
	v_mov_b32_e32 v110, v68
	v_mov_b32_e32 v111, v68
	v_mov_b32_e32 v12, v68
	v_mov_b32_e32 v13, v68
	v_mov_b32_e32 v14, v68
	v_mov_b32_e32 v15, v68
	v_mov_b32_e32 v64, v68
	v_mov_b32_e32 v65, v68
	v_mov_b32_e32 v66, v68
	v_mov_b32_e32 v67, v68
	v_mov_b32_e32 v8, v68
	v_mov_b32_e32 v9, v68
	v_mov_b32_e32 v10, v68
	v_mov_b32_e32 v11, v68
	v_mov_b32_e32 v56, v68
	v_mov_b32_e32 v57, v68
	v_mov_b32_e32 v58, v68
	v_mov_b32_e32 v59, v68
	v_mov_b32_e32 v4, v68
	v_mov_b32_e32 v5, v68
	v_mov_b32_e32 v6, v68
	v_mov_b32_e32 v7, v68
	v_mov_b32_e32 v52, v68
	v_mov_b32_e32 v53, v68
	v_mov_b32_e32 v54, v68
	v_mov_b32_e32 v55, v68
	v_mov_b32_e32 v0, v68
	v_mov_b32_e32 v1, v68
	v_mov_b32_e32 v2, v68
	v_mov_b32_e32 v3, v68
	v_mov_b32_e32 v48, v68
	v_mov_b32_e32 v49, v68
	v_mov_b32_e32 v50, v68
	v_mov_b32_e32 v51, v68
	v_mov_b32_e32 v112, v68
	s_waitcnt lgkmcnt(0)
	v_mov_b32_e32 v113, v68
	v_mov_b32_e32 v114, v68
	v_mov_b32_e32 v115, v68
	v_mov_b32_e32 v80, v68
	v_mov_b32_e32 v81, v68
	v_mov_b32_e32 v82, v68
	v_mov_b32_e32 v83, v68
	v_mov_b32_e32 v116, v68
	v_mov_b32_e32 v117, v68
	v_mov_b32_e32 v118, v68
	v_mov_b32_e32 v119, v68
	v_mov_b32_e32 v72, v68
	v_mov_b32_e32 v73, v68
	v_mov_b32_e32 v74, v68
	v_mov_b32_e32 v75, v68
	v_mov_b32_e32 v120, v68
	v_mov_b32_e32 v121, v68
	v_mov_b32_e32 v122, v68
	v_mov_b32_e32 v123, v68
	v_mov_b32_e32 v124, v68
	v_mov_b32_e32 v125, v68
	v_mov_b32_e32 v126, v68
	v_mov_b32_e32 v127, v68
	v_mov_b32_e32 v28, v68
	v_mov_b32_e32 v29, v68
	v_mov_b32_e32 v30, v68
	v_mov_b32_e32 v31, v68
	v_mov_b32_e32 v96, v68
	v_mov_b32_e32 v97, v68
	v_mov_b32_e32 v98, v68
	v_mov_b32_e32 v99, v68
	v_mov_b32_e32 v24, v68
	v_mov_b32_e32 v25, v68
	v_mov_b32_e32 v26, v68
	v_mov_b32_e32 v27, v68
	v_mov_b32_e32 v92, v68
	v_mov_b32_e32 v93, v68
	v_mov_b32_e32 v94, v68
	v_mov_b32_e32 v95, v68
	v_mov_b32_e32 v20, v68
	v_mov_b32_e32 v21, v68
	v_mov_b32_e32 v22, v68
	v_mov_b32_e32 v23, v68
	v_mov_b32_e32 v88, v68
	v_mov_b32_e32 v89, v68
	v_mov_b32_e32 v90, v68
	v_mov_b32_e32 v91, v68
	v_mov_b32_e32 v16, v68
	v_mov_b32_e32 v17, v68
	v_mov_b32_e32 v18, v68
	v_mov_b32_e32 v19, v68
	v_mov_b32_e32 v84, v68
	v_mov_b32_e32 v85, v68
	v_mov_b32_e32 v86, v68
	v_mov_b32_e32 v87, v68
	v_readlane_b32 s98, v251, 42
	s_cmp_lt_u32 s98, 4
	s_cbranch_scc0 .Lcm4_skip
	v_mbcnt_lo_u32_b32 v230, -1, 0
	v_mbcnt_hi_u32_b32 v230, -1, v230
	v_lshlrev_b32_e32 v230, 2, v230
	s_lshr_b32 s99, s98, 1
	s_mul_i32 s99, s99, 0xac00
	s_and_b32 s100, s98, 1
	s_lshl_b32 s100, s100, 8
	s_add_i32 s99, s99, s100
	s_lshl_b32 s100, s4, 9
	s_add_i32 s99, s99, s100
	v_readlane_b32 s100, v251, 19
	v_readlane_b32 s101, v251, 20
	s_add_u32 s100, s100, 0x40000
	s_addc_u32 s101, s101, 0
	s_add_u32 s100, s100, s99
	s_addc_u32 s101, s101, 0
	s_lshl_b32 s99, s98, 8
	s_add_i32 m0, s99, 0x21000
	s_nop 0
	global_load_lds_dword v230, s[100:101]
.Lcm4_skip:
.LBB0_800:
	ds_read_b128 v[128:131], v187
	ds_read_b128 v[132:135], v187 offset:1024
	ds_read_b128 v[136:139], v187 offset:2048
	ds_read_b128 v[140:143], v187 offset:3072
	ds_read_b128 v[144:147], v188
	ds_read_b128 v[148:151], v188 offset:1024
	ds_read_b128 v[152:155], v188 offset:2048
	ds_read_b128 v[156:159], v188 offset:3072
	s_add_u32 s9, s6, 0xfff80080
	s_addc_u32 s50, s7, -1
	s_cmp_eq_u32 s8, 28
	s_cselect_b32 vcc_hi, s5, s50
	s_cselect_b32 vcc_lo, s10, s9
	s_cselect_b32 s51, s11, s78
	s_cselect_b32 s50, s73, s75
	s_add_i32 m0, s65, 0xc000
	ds_read_b128 v[160:163], v189
	ds_read_b128 v[164:167], v189 offset:1024
	ds_read_b128 v[168:171], v189 offset:2048
	ds_read_b128 v[192:195], v189 offset:3072
	ds_read_b128 v[196:199], v189 offset:4096
	ds_read_b128 v[200:203], v189 offset:5120
	ds_read_b128 v[204:207], v189 offset:6144
	ds_read_b128 v[208:211], v189 offset:7168
	global_load_lds_dwordx4 v178, s[6:7]
	s_add_i32 m0, s65, 0xe000
	s_nop 0
	s_add_u32 s98, s6, s36
	s_addc_u32 s99, s7, s37
	global_load_lds_dwordx4 v178, s[98:99]
	s_waitcnt vmcnt(8)
	s_waitcnt lgkmcnt(0)
	s_barrier
	s_setprio 1
	s_waitcnt lgkmcnt(0)
	v_mfma_i32_16x16x64_i8 v[84:87], v[128:131], v[160:163], v[84:87]
	v_mfma_i32_16x16x64_i8 v[84:87], v[132:135], v[164:167], v[84:87]
	v_mfma_i32_16x16x64_i8 v[16:19], v[136:139], v[160:163], v[16:19]
	v_mfma_i32_16x16x64_i8 v[16:19], v[140:143], v[164:167], v[16:19]
	v_mfma_i32_16x16x64_i8 v[88:91], v[128:131], v[168:171], v[88:91]
	v_mfma_i32_16x16x64_i8 v[88:91], v[132:135], v[192:195], v[88:91]
	v_mfma_i32_16x16x64_i8 v[20:23], v[136:139], v[168:171], v[20:23]
	v_mfma_i32_16x16x64_i8 v[20:23], v[140:143], v[192:195], v[20:23]
	v_mfma_i32_16x16x64_i8 v[92:95], v[128:131], v[196:199], v[92:95]
	v_mfma_i32_16x16x64_i8 v[92:95], v[132:135], v[200:203], v[92:95]
	v_mfma_i32_16x16x64_i8 v[24:27], v[136:139], v[196:199], v[24:27]
	v_mfma_i32_16x16x64_i8 v[24:27], v[140:143], v[200:203], v[24:27]
	v_mfma_i32_16x16x64_i8 v[96:99], v[128:131], v[204:207], v[96:99]
	v_mfma_i32_16x16x64_i8 v[96:99], v[132:135], v[208:211], v[96:99]
	v_mfma_i32_16x16x64_i8 v[28:31], v[136:139], v[204:207], v[28:31]
	v_mfma_i32_16x16x64_i8 v[28:31], v[140:143], v[208:211], v[28:31]
	s_setprio 0
	s_setprio 1
	v_mfma_i32_16x16x64_i8 v[124:127], v[144:147], v[160:163], v[124:127]
	v_mfma_i32_16x16x64_i8 v[124:127], v[148:151], v[164:167], v[124:127]
	v_mfma_i32_16x16x64_i8 v[68:71], v[152:155], v[160:163], v[68:71]
	v_mfma_i32_16x16x64_i8 v[68:71], v[156:159], v[164:167], v[68:71]
	v_mfma_i32_16x16x64_i8 v[120:123], v[144:147], v[168:171], v[120:123]
	v_mfma_i32_16x16x64_i8 v[120:123], v[148:151], v[192:195], v[120:123]
	v_mfma_i32_16x16x64_i8 v[72:75], v[152:155], v[168:171], v[72:75]
	v_mfma_i32_16x16x64_i8 v[72:75], v[156:159], v[192:195], v[72:75]
	v_mfma_i32_16x16x64_i8 v[116:119], v[144:147], v[196:199], v[116:119]
	v_mfma_i32_16x16x64_i8 v[116:119], v[148:151], v[200:203], v[116:119]
	v_mfma_i32_16x16x64_i8 v[80:83], v[152:155], v[196:199], v[80:83]
	v_mfma_i32_16x16x64_i8 v[80:83], v[156:159], v[200:203], v[80:83]
	s_setprio 2
	s_barrier
	v_mfma_i32_16x16x64_i8 v[112:115], v[144:147], v[204:207], v[112:115]
	v_mfma_i32_16x16x64_i8 v[112:115], v[148:151], v[208:211], v[112:115]
	v_mfma_i32_16x16x64_i8 v[60:63], v[152:155], v[204:207], v[60:63]
	v_mfma_i32_16x16x64_i8 v[60:63], v[156:159], v[208:211], v[60:63]
	s_setprio 0
	s_add_i32 s9, s80, s33
	s_mov_b64 s[100:101], s[50:51]
	s_mov_b32 m0, s9
	ds_read_b128 v[160:163], v189 offset:16384
	ds_read_b128 v[164:167], v189 offset:17408
	ds_read_b128 v[168:171], v189 offset:18432
	ds_read_b128 v[192:195], v189 offset:19456
	ds_read_b128 v[196:199], v189 offset:20480
	ds_read_b128 v[200:203], v189 offset:21504
	ds_read_b128 v[204:207], v189 offset:22528
	ds_read_b128 v[208:211], v189 offset:23552
	global_load_lds_dwordx4 v174, s[50:51]
	s_add_i32 m0, s9, 0x2000
	s_add_i32 s9, s81, s33
	s_add_u32 s98, s50, s36
	s_addc_u32 s99, s51, s37
	global_load_lds_dwordx4 v174, s[98:99]
	s_mov_b32 m0, s9
	s_nop 0
	s_add_u32 s98, s50, s38
	s_addc_u32 s99, s51, s39
	global_load_lds_dwordx4 v174, s[98:99]
	s_add_i32 m0, s9, 0x2000
	s_nop 0
	s_add_u32 s98, s50, s40
	s_addc_u32 s99, s51, s41
	global_load_lds_dwordx4 v174, s[98:99]
	s_mov_b32 m0, s65
	s_nop 0
	global_load_lds_dwordx4 v172, vcc
	s_mov_b32 m0, s67
	s_nop 0
	s_add_u32 s98, vcc_lo, s36
	s_addc_u32 s99, vcc_hi, s37
	global_load_lds_dwordx4 v172, s[98:99]
	s_waitcnt vmcnt(8)
	s_waitcnt lgkmcnt(0)
	s_barrier
	s_setprio 1
	s_waitcnt lgkmcnt(0)
	v_mfma_i32_16x16x64_i8 v[48:51], v[128:131], v[160:163], v[48:51]
	v_mfma_i32_16x16x64_i8 v[48:51], v[132:135], v[164:167], v[48:51]
	v_mfma_i32_16x16x64_i8 v[0:3], v[136:139], v[160:163], v[0:3]
	v_mfma_i32_16x16x64_i8 v[0:3], v[140:143], v[164:167], v[0:3]
	v_mfma_i32_16x16x64_i8 v[52:55], v[128:131], v[168:171], v[52:55]
	v_mfma_i32_16x16x64_i8 v[52:55], v[132:135], v[192:195], v[52:55]
	v_mfma_i32_16x16x64_i8 v[4:7], v[136:139], v[168:171], v[4:7]
	v_mfma_i32_16x16x64_i8 v[4:7], v[140:143], v[192:195], v[4:7]
	v_mfma_i32_16x16x64_i8 v[56:59], v[128:131], v[196:199], v[56:59]
	v_mfma_i32_16x16x64_i8 v[56:59], v[132:135], v[200:203], v[56:59]
	v_mfma_i32_16x16x64_i8 v[8:11], v[136:139], v[196:199], v[8:11]
	v_mfma_i32_16x16x64_i8 v[8:11], v[140:143], v[200:203], v[8:11]
	v_mfma_i32_16x16x64_i8 v[64:67], v[128:131], v[204:207], v[64:67]
	v_mfma_i32_16x16x64_i8 v[64:67], v[132:135], v[208:211], v[64:67]
	v_mfma_i32_16x16x64_i8 v[12:15], v[136:139], v[204:207], v[12:15]
	v_mfma_i32_16x16x64_i8 v[12:15], v[140:143], v[208:211], v[12:15]
	s_setprio 0
	s_setprio 1
	v_mfma_i32_16x16x64_i8 v[108:111], v[144:147], v[160:163], v[108:111]
	v_mfma_i32_16x16x64_i8 v[108:111], v[148:151], v[164:167], v[108:111]
	v_mfma_i32_16x16x64_i8 v[44:47], v[152:155], v[160:163], v[44:47]
	v_mfma_i32_16x16x64_i8 v[44:47], v[156:159], v[164:167], v[44:47]
	v_mfma_i32_16x16x64_i8 v[104:107], v[144:147], v[168:171], v[104:107]
	v_mfma_i32_16x16x64_i8 v[104:107], v[148:151], v[192:195], v[104:107]
	v_mfma_i32_16x16x64_i8 v[40:43], v[152:155], v[168:171], v[40:43]
	v_mfma_i32_16x16x64_i8 v[40:43], v[156:159], v[192:195], v[40:43]
	v_mfma_i32_16x16x64_i8 v[100:103], v[144:147], v[196:199], v[100:103]
	v_mfma_i32_16x16x64_i8 v[100:103], v[148:151], v[200:203], v[100:103]
	v_mfma_i32_16x16x64_i8 v[32:35], v[152:155], v[196:199], v[32:35]
	v_mfma_i32_16x16x64_i8 v[32:35], v[156:159], v[200:203], v[32:35]
	s_setprio 2
	s_barrier
	v_mfma_i32_16x16x64_i8 v[76:79], v[144:147], v[204:207], v[76:79]
	v_mfma_i32_16x16x64_i8 v[76:79], v[148:151], v[208:211], v[76:79]
	v_mfma_i32_16x16x64_i8 v[36:39], v[152:155], v[204:207], v[36:39]
	v_mfma_i32_16x16x64_i8 v[36:39], v[156:159], v[208:211], v[36:39]
	s_setprio 0
	s_add_i32 s9, 0, 0x18000
	s_add_i32 s50, 0, 0x1c000
	v_add_u32_e32 v140, s9, v186
	v_add_u32_e32 v156, s50, v186
	ds_read_b128 v[128:131], v140
	ds_read_b128 v[132:135], v140 offset:1024
	ds_read_b128 v[136:139], v140 offset:2048
	ds_read_b128 v[140:143], v140 offset:3072
	ds_read_b128 v[144:147], v156
	ds_read_b128 v[148:151], v156 offset:1024
	ds_read_b128 v[152:155], v156 offset:2048
	ds_read_b128 v[156:159], v156 offset:3072
	s_mov_b32 m0, s71
	ds_read_b128 v[160:163], v189 offset:32768
	ds_read_b128 v[164:167], v189 offset:33792
	ds_read_b128 v[168:171], v189 offset:34816
	ds_read_b128 v[192:195], v189 offset:35840
	ds_read_b128 v[196:199], v189 offset:36864
	ds_read_b128 v[200:203], v189 offset:37888
	ds_read_b128 v[204:207], v189 offset:38912
	ds_read_b128 v[208:211], v189 offset:39936
	s_add_u32 s98, vcc_lo, s38
	s_addc_u32 s99, vcc_hi, s39
	global_load_lds_dwordx4 v172, s[98:99]
	s_mov_b32 m0, s82
	s_nop 0
	s_add_u32 s98, vcc_lo, s40
	s_addc_u32 s99, vcc_hi, s41
	global_load_lds_dwordx4 v172, s[98:99]
	s_waitcnt vmcnt(8)
	s_waitcnt lgkmcnt(0)
	s_barrier
	s_setprio 1
	s_waitcnt lgkmcnt(0)
	v_mfma_i32_16x16x64_i8 v[84:87], v[128:131], v[160:163], v[84:87]
	v_mfma_i32_16x16x64_i8 v[84:87], v[132:135], v[164:167], v[84:87]
	v_mfma_i32_16x16x64_i8 v[16:19], v[136:139], v[160:163], v[16:19]
	v_mfma_i32_16x16x64_i8 v[16:19], v[140:143], v[164:167], v[16:19]
	v_mfma_i32_16x16x64_i8 v[88:91], v[128:131], v[168:171], v[88:91]
	v_mfma_i32_16x16x64_i8 v[88:91], v[132:135], v[192:195], v[88:91]
	v_mfma_i32_16x16x64_i8 v[20:23], v[136:139], v[168:171], v[20:23]
	v_mfma_i32_16x16x64_i8 v[20:23], v[140:143], v[192:195], v[20:23]
	v_mfma_i32_16x16x64_i8 v[92:95], v[128:131], v[196:199], v[92:95]
	v_mfma_i32_16x16x64_i8 v[92:95], v[132:135], v[200:203], v[92:95]
	v_mfma_i32_16x16x64_i8 v[24:27], v[136:139], v[196:199], v[24:27]
	v_mfma_i32_16x16x64_i8 v[24:27], v[140:143], v[200:203], v[24:27]
	v_mfma_i32_16x16x64_i8 v[96:99], v[128:131], v[204:207], v[96:99]
	v_mfma_i32_16x16x64_i8 v[96:99], v[132:135], v[208:211], v[96:99]
	v_mfma_i32_16x16x64_i8 v[28:31], v[136:139], v[204:207], v[28:31]
	v_mfma_i32_16x16x64_i8 v[28:31], v[140:143], v[208:211], v[28:31]
	s_setprio 0
	s_setprio 1
	v_mfma_i32_16x16x64_i8 v[124:127], v[144:147], v[160:163], v[124:127]
	v_mfma_i32_16x16x64_i8 v[124:127], v[148:151], v[164:167], v[124:127]
	v_mfma_i32_16x16x64_i8 v[68:71], v[152:155], v[160:163], v[68:71]
	v_mfma_i32_16x16x64_i8 v[68:71], v[156:159], v[164:167], v[68:71]
	v_mfma_i32_16x16x64_i8 v[120:123], v[144:147], v[168:171], v[120:123]
	v_mfma_i32_16x16x64_i8 v[120:123], v[148:151], v[192:195], v[120:123]
	v_mfma_i32_16x16x64_i8 v[72:75], v[152:155], v[168:171], v[72:75]
	v_mfma_i32_16x16x64_i8 v[72:75], v[156:159], v[192:195], v[72:75]
	v_mfma_i32_16x16x64_i8 v[116:119], v[144:147], v[196:199], v[116:119]
	v_mfma_i32_16x16x64_i8 v[116:119], v[148:151], v[200:203], v[116:119]
	v_mfma_i32_16x16x64_i8 v[80:83], v[152:155], v[196:199], v[80:83]
	v_mfma_i32_16x16x64_i8 v[80:83], v[156:159], v[200:203], v[80:83]
	s_setprio 2
	s_barrier
	v_mfma_i32_16x16x64_i8 v[112:115], v[144:147], v[204:207], v[112:115]
	v_mfma_i32_16x16x64_i8 v[112:115], v[148:151], v[208:211], v[112:115]
	v_mfma_i32_16x16x64_i8 v[60:63], v[152:155], v[204:207], v[60:63]
	v_mfma_i32_16x16x64_i8 v[60:63], v[156:159], v[208:211], v[60:63]
	s_setprio 0
	s_add_i32 s9, s9, s33
	s_mov_b32 m0, s9
	ds_read_b128 v[160:163], v189 offset:49152
	ds_read_b128 v[164:167], v189 offset:50176
	ds_read_b128 v[168:171], v189 offset:51200
	ds_read_b128 v[192:195], v189 offset:52224
	ds_read_b128 v[196:199], v189 offset:53248
	ds_read_b128 v[200:203], v189 offset:54272
	ds_read_b128 v[204:207], v189 offset:55296
	ds_read_b128 v[208:211], v189 offset:56320
	s_add_u32 s98, s100, s44
	s_addc_u32 s99, s101, s45
	global_load_lds_dwordx4 v174, s[98:99]
	s_add_i32 m0, s9, 0x2000
	s_add_i32 s9, s50, s33
	s_add_u32 s98, s100, s46
	s_addc_u32 s99, s101, s47
	global_load_lds_dwordx4 v174, s[98:99]
	s_mov_b32 m0, s9
	s_add_u32 s98, s100, s48
	s_addc_u32 s99, s101, s49
	global_load_lds_dwordx4 v174, s[98:99]
	s_add_i32 m0, s9, 0x2000
	s_nop 0
	s_add_u32 s98, s100, s52
	s_addc_u32 s99, s101, s53
	global_load_lds_dwordx4 v174, s[98:99]
	s_mov_b32 m0, s90
	s_nop 0
	s_add_u32 s98, vcc_lo, s44
	s_addc_u32 s99, vcc_hi, s45
	global_load_lds_dwordx4 v172, s[98:99]
	s_mov_b32 m0, s91
	s_nop 0
	s_add_u32 s98, vcc_lo, s46
	s_addc_u32 s99, vcc_hi, s47
	global_load_lds_dwordx4 v172, s[98:99]
	s_waitcnt vmcnt(8)
	s_waitcnt lgkmcnt(0)
	s_barrier
	s_setprio 1
	s_waitcnt lgkmcnt(0)
	v_mfma_i32_16x16x64_i8 v[48:51], v[128:131], v[160:163], v[48:51]
	v_mfma_i32_16x16x64_i8 v[48:51], v[132:135], v[164:167], v[48:51]
	v_mfma_i32_16x16x64_i8 v[0:3], v[136:139], v[160:163], v[0:3]
	v_mfma_i32_16x16x64_i8 v[0:3], v[140:143], v[164:167], v[0:3]
	v_mfma_i32_16x16x64_i8 v[52:55], v[128:131], v[168:171], v[52:55]
	v_mfma_i32_16x16x64_i8 v[52:55], v[132:135], v[192:195], v[52:55]
	v_mfma_i32_16x16x64_i8 v[4:7], v[136:139], v[168:171], v[4:7]
	v_mfma_i32_16x16x64_i8 v[4:7], v[140:143], v[192:195], v[4:7]
	v_mfma_i32_16x16x64_i8 v[56:59], v[128:131], v[196:199], v[56:59]
	v_mfma_i32_16x16x64_i8 v[56:59], v[132:135], v[200:203], v[56:59]
	v_mfma_i32_16x16x64_i8 v[8:11], v[136:139], v[196:199], v[8:11]
	v_mfma_i32_16x16x64_i8 v[8:11], v[140:143], v[200:203], v[8:11]
	v_mfma_i32_16x16x64_i8 v[64:67], v[128:131], v[204:207], v[64:67]
	v_mfma_i32_16x16x64_i8 v[64:67], v[132:135], v[208:211], v[64:67]
	v_mfma_i32_16x16x64_i8 v[12:15], v[136:139], v[204:207], v[12:15]
	v_mfma_i32_16x16x64_i8 v[12:15], v[140:143], v[208:211], v[12:15]
	s_setprio 0
	s_setprio 1
	v_mfma_i32_16x16x64_i8 v[108:111], v[144:147], v[160:163], v[108:111]
	v_mfma_i32_16x16x64_i8 v[108:111], v[148:151], v[164:167], v[108:111]
	v_mfma_i32_16x16x64_i8 v[44:47], v[152:155], v[160:163], v[44:47]
	v_mfma_i32_16x16x64_i8 v[44:47], v[156:159], v[164:167], v[44:47]
	v_mfma_i32_16x16x64_i8 v[104:107], v[144:147], v[168:171], v[104:107]
	v_mfma_i32_16x16x64_i8 v[104:107], v[148:151], v[192:195], v[104:107]
	v_mfma_i32_16x16x64_i8 v[40:43], v[152:155], v[168:171], v[40:43]
	v_mfma_i32_16x16x64_i8 v[40:43], v[156:159], v[192:195], v[40:43]
	v_mfma_i32_16x16x64_i8 v[100:103], v[144:147], v[196:199], v[100:103]
	v_mfma_i32_16x16x64_i8 v[100:103], v[148:151], v[200:203], v[100:103]
	v_mfma_i32_16x16x64_i8 v[32:35], v[152:155], v[196:199], v[32:35]
	v_mfma_i32_16x16x64_i8 v[32:35], v[156:159], v[200:203], v[32:35]
	s_setprio 2
	s_barrier
	v_mfma_i32_16x16x64_i8 v[76:79], v[144:147], v[204:207], v[76:79]
	v_mfma_i32_16x16x64_i8 v[76:79], v[148:151], v[208:211], v[76:79]
	v_mfma_i32_16x16x64_i8 v[36:39], v[152:155], v[204:207], v[36:39]
	v_mfma_i32_16x16x64_i8 v[36:39], v[156:159], v[208:211], v[36:39]
	s_setprio 0
	s_add_i32 s8, s8, 2
	s_add_u32 s75, s75, 0x100
	s_addc_u32 s78, s78, 0
	s_add_u32 s6, s6, 0x100
	s_addc_u32 s7, s7, 0
	s_cmp_gt_u32 s8, 29
	s_cbranch_scc0 .LBB0_800
	s_and_b64 vcc, exec, s[54:55]
	s_cbranch_vccz .LBB0_803
	s_barrier

.LBB0_807:
	s_lshl_b32 s4, s4, 7
	s_ashr_i32 s5, s4, 31
	v_ashrrev_i32_e32 v147, 4, v128
	s_lshl_b64 s[6:7], s[4:5], 2
	v_lshlrev_b32_e32 v140, 3, v147
	s_add_u32 s6, s59, s6
	v_and_b32_e32 v191, 15, v128
	v_ashrrev_i32_e32 v141, 31, v140
	s_addc_u32 s7, s24, s7
	v_lshl_add_u32 v128, v191, 2, s25
	v_lshl_add_u64 v[132:133], v[140:141], 2, s[6:7]
	ds_read2_b32 v[144:145], v128 offset1:16
	ds_read2_b32 v[142:143], v128 offset0:32 offset1:48
	ds_read2_b32 v[138:139], v128 offset0:128 offset1:144
	ds_read2_b32 v[136:137], v128 offset0:160 offset1:176
	s_lshl_b32 s98, s69, 2
	s_add_i32 s98, s98, 0x21000
	v_lshl_add_u32 v230, v140, 2, s98
	ds_read_b128 v[128:131], v230
	v_cvt_f32_i32_e32 v85, v85
	v_cvt_f32_i32_e32 v84, v84
	v_cvt_f32_i32_e32 v89, v89
	v_cvt_f32_i32_e32 v88, v88
	v_cvt_f32_i32_e32 v87, v87
	v_cvt_f32_i32_e32 v86, v86
	v_cvt_f32_i32_e32 v93, v93
	v_cvt_f32_i32_e32 v92, v92
	v_cvt_f32_i32_e32 v91, v91
	v_cvt_f32_i32_e32 v90, v90
	s_waitcnt lgkmcnt(0)
	v_mov_b32_e32 v148, v145
	v_cvt_f32_i32_e32 v95, v95
	v_cvt_f32_i32_e32 v94, v94
	v_cvt_f32_i32_e32 v97, v97
	v_cvt_f32_i32_e32 v96, v96
	v_cvt_f32_i32_e32 v99, v99
	v_cvt_f32_i32_e32 v98, v98
	v_cvt_f32_i32_e32 v49, v49
	v_cvt_f32_i32_e32 v48, v48
	v_cvt_f32_i32_e32 v51, v51
	v_cvt_f32_i32_e32 v50, v50
	v_cvt_f32_i32_e32 v53, v53
	v_cvt_f32_i32_e32 v52, v52
	v_cvt_f32_i32_e32 v55, v55
	v_cvt_f32_i32_e32 v54, v54
	v_cvt_f32_i32_e32 v57, v57
	v_cvt_f32_i32_e32 v56, v56
	v_cvt_f32_i32_e32 v59, v59
	v_cvt_f32_i32_e32 v58, v58
	v_cvt_f32_i32_e32 v65, v65
	v_cvt_f32_i32_e32 v64, v64
	v_cvt_f32_i32_e32 v67, v67
	v_cvt_f32_i32_e32 v66, v66
	v_mov_b32_e32 v146, v137
	s_waitcnt lgkmcnt(0)
	v_pk_mul_f32 v[150:151], v[144:145], v[128:129] op_sel_hi:[0,1]
	v_pk_mul_f32 v[84:85], v[150:151], v[84:85]
	v_pk_mul_f32 v[150:151], v[148:149], v[128:129] op_sel_hi:[0,1]
	v_pk_mul_f32 v[134:135], v[144:145], v[130:131] op_sel_hi:[0,1]
	v_pk_mul_f32 v[88:89], v[150:151], v[88:89]
	v_pk_mul_f32 v[150:151], v[142:143], v[128:129] op_sel_hi:[0,1]
	v_pk_mul_f32 v[86:87], v[134:135], v[86:87]
	v_pk_mul_f32 v[134:135], v[148:149], v[130:131] op_sel_hi:[0,1]
	v_pk_mul_f32 v[92:93], v[150:151], v[92:93]
	v_mov_b32_e32 v150, v143
	v_pk_mul_f32 v[90:91], v[134:135], v[90:91]
	v_pk_mul_f32 v[134:135], v[142:143], v[130:131] op_sel_hi:[0,1]
	v_pk_mul_f32 v[152:153], v[150:151], v[128:129] op_sel_hi:[0,1]
	v_pk_mul_f32 v[94:95], v[134:135], v[94:95]
	v_pk_mul_f32 v[134:135], v[150:151], v[130:131] op_sel_hi:[0,1]
	v_pk_mul_f32 v[96:97], v[152:153], v[96:97]
	v_pk_mul_f32 v[152:153], v[138:139], v[128:129] op_sel_hi:[0,1]
	v_pk_mul_f32 v[98:99], v[134:135], v[98:99]
	v_pk_mul_f32 v[134:135], v[138:139], v[130:131] op_sel_hi:[0,1]
	v_pk_mul_f32 v[48:49], v[152:153], v[48:49]
	v_mov_b32_e32 v152, v139
	v_pk_mul_f32 v[50:51], v[134:135], v[50:51]
	v_pk_mul_f32 v[134:135], v[152:153], v[130:131] op_sel_hi:[0,1]
	v_pk_mul_f32 v[154:155], v[152:153], v[128:129] op_sel_hi:[0,1]
	v_pk_mul_f32 v[54:55], v[134:135], v[54:55]
	v_pk_mul_f32 v[52:53], v[154:155], v[52:53]
	v_pk_mul_f32 v[134:135], v[136:137], v[130:131] op_sel_hi:[0,1]
	v_pk_mul_f32 v[154:155], v[136:137], v[128:129] op_sel_hi:[0,1]
	v_pk_mul_f32 v[130:131], v[130:131], v[146:147] op_sel_hi:[1,0]
	v_pk_mul_f32 v[128:129], v[128:129], v[146:147] op_sel_hi:[1,0]
	v_pk_mul_f32 v[58:59], v[134:135], v[58:59]
	v_pk_mul_f32 v[56:57], v[154:155], v[56:57]
	v_pk_mul_f32 v[66:67], v[130:131], v[66:67]
	v_pk_mul_f32 v[64:65], v[128:129], v[64:65]
	s_nop 0
	ds_read_b128 v[128:131], v230 offset:16
	v_cvt_f32_i32_e32 v17, v17
	v_cvt_f32_i32_e32 v16, v16
	v_cvt_f32_i32_e32 v19, v19
	v_cvt_f32_i32_e32 v18, v18
	v_cvt_f32_i32_e32 v21, v21
	v_cvt_f32_i32_e32 v20, v20
	v_cvt_f32_i32_e32 v23, v23
	v_cvt_f32_i32_e32 v22, v22
	v_cvt_f32_i32_e32 v25, v25
	v_cvt_f32_i32_e32 v24, v24
	v_cvt_f32_i32_e32 v27, v27
	v_cvt_f32_i32_e32 v26, v26
	v_cvt_f32_i32_e32 v29, v29
	v_cvt_f32_i32_e32 v28, v28
	v_cvt_f32_i32_e32 v31, v31
	v_cvt_f32_i32_e32 v30, v30
	v_cvt_f32_i32_e32 v1, v1
	v_cvt_f32_i32_e32 v0, v0
	v_cvt_f32_i32_e32 v3, v3
	v_cvt_f32_i32_e32 v2, v2
	v_cvt_f32_i32_e32 v5, v5
	v_cvt_f32_i32_e32 v4, v4
	v_cvt_f32_i32_e32 v7, v7
	v_cvt_f32_i32_e32 v6, v6
	v_cvt_f32_i32_e32 v9, v9
	v_cvt_f32_i32_e32 v8, v8
	v_cvt_f32_i32_e32 v11, v11
	v_cvt_f32_i32_e32 v10, v10
	v_cvt_f32_i32_e32 v13, v13
	v_cvt_f32_i32_e32 v12, v12
	v_cvt_f32_i32_e32 v15, v15
	v_cvt_f32_i32_e32 v14, v14
	s_waitcnt lgkmcnt(0)
	v_pk_mul_f32 v[134:135], v[144:145], v[130:131] op_sel_hi:[0,1]
	v_pk_mul_f32 v[154:155], v[144:145], v[128:129] op_sel_hi:[0,1]
	v_pk_mul_f32 v[18:19], v[134:135], v[18:19]
	v_pk_mul_f32 v[16:17], v[154:155], v[16:17]
	v_pk_mul_f32 v[134:135], v[148:149], v[130:131] op_sel_hi:[0,1]
	v_pk_mul_f32 v[154:155], v[148:149], v[128:129] op_sel_hi:[0,1]
	v_pk_mul_f32 v[22:23], v[134:135], v[22:23]
	v_pk_mul_f32 v[20:21], v[154:155], v[20:21]
	v_pk_mul_f32 v[134:135], v[142:143], v[130:131] op_sel_hi:[0,1]
	v_pk_mul_f32 v[154:155], v[142:143], v[128:129] op_sel_hi:[0,1]
	v_pk_mul_f32 v[26:27], v[134:135], v[26:27]
	v_pk_mul_f32 v[24:25], v[154:155], v[24:25]
	v_pk_mul_f32 v[134:135], v[150:151], v[130:131] op_sel_hi:[0,1]
	v_pk_mul_f32 v[154:155], v[150:151], v[128:129] op_sel_hi:[0,1]
	v_pk_mul_f32 v[30:31], v[134:135], v[30:31]
	v_pk_mul_f32 v[28:29], v[154:155], v[28:29]
	v_pk_mul_f32 v[134:135], v[138:139], v[130:131] op_sel_hi:[0,1]
	v_pk_mul_f32 v[154:155], v[138:139], v[128:129] op_sel_hi:[0,1]
	v_pk_mul_f32 v[2:3], v[134:135], v[2:3]
	v_pk_mul_f32 v[0:1], v[154:155], v[0:1]
	v_pk_mul_f32 v[134:135], v[152:153], v[130:131] op_sel_hi:[0,1]
	v_pk_mul_f32 v[154:155], v[152:153], v[128:129] op_sel_hi:[0,1]
	v_pk_mul_f32 v[6:7], v[134:135], v[6:7]
	v_pk_mul_f32 v[4:5], v[154:155], v[4:5]
	v_pk_mul_f32 v[134:135], v[136:137], v[130:131] op_sel_hi:[0,1]
	v_pk_mul_f32 v[154:155], v[136:137], v[128:129] op_sel_hi:[0,1]
	v_pk_mul_f32 v[130:131], v[146:147], v[130:131] op_sel_hi:[0,1]
	v_pk_mul_f32 v[128:129], v[146:147], v[128:129] op_sel_hi:[0,1]
	v_pk_mul_f32 v[10:11], v[134:135], v[10:11]
	v_pk_mul_f32 v[8:9], v[154:155], v[8:9]
	v_pk_mul_f32 v[14:15], v[130:131], v[14:15]
	v_pk_mul_f32 v[12:13], v[128:129], v[12:13]
	s_nop 0
	s_mov_b32 s5, 0xa000
	v_add_co_u32_e32 v154, vcc, s5, v132
	v_cvt_f32_i32_e32 v125, v125
	s_nop 0
	v_addc_co_u32_e32 v155, vcc, 0, v133, vcc
	ds_read_b128 v[132:135], v230 offset:512
	v_cvt_f32_i32_e32 v124, v124
	v_cvt_f32_i32_e32 v127, v127
	v_cvt_f32_i32_e32 v126, v126
	v_cvt_f32_i32_e32 v121, v121
	v_cvt_f32_i32_e32 v120, v120
	v_cvt_f32_i32_e32 v123, v123
	v_cvt_f32_i32_e32 v122, v122
	v_cvt_f32_i32_e32 v117, v117
	v_cvt_f32_i32_e32 v116, v116
	v_cvt_f32_i32_e32 v119, v119
	v_cvt_f32_i32_e32 v118, v118
	v_cvt_f32_i32_e32 v113, v113
	v_cvt_f32_i32_e32 v112, v112
	v_cvt_f32_i32_e32 v115, v115
	v_cvt_f32_i32_e32 v114, v114
	v_cvt_f32_i32_e32 v109, v109
	v_cvt_f32_i32_e32 v108, v108
	v_cvt_f32_i32_e32 v111, v111
	v_cvt_f32_i32_e32 v110, v110
	v_cvt_f32_i32_e32 v105, v105
	v_cvt_f32_i32_e32 v104, v104
	v_cvt_f32_i32_e32 v107, v107
	v_cvt_f32_i32_e32 v106, v106
	v_cvt_f32_i32_e32 v103, v103
	v_cvt_f32_i32_e32 v102, v102
	v_cvt_f32_i32_e32 v101, v101
	v_cvt_f32_i32_e32 v100, v100
	v_cvt_f32_i32_e32 v77, v77
	v_cvt_f32_i32_e32 v76, v76
	v_cvt_f32_i32_e32 v79, v79
	v_cvt_f32_i32_e32 v78, v78
	s_waitcnt lgkmcnt(0)
	v_pk_mul_f32 v[128:129], v[144:145], v[134:135] op_sel_hi:[0,1]
	v_pk_mul_f32 v[156:157], v[144:145], v[132:133] op_sel_hi:[0,1]
	v_pk_mul_f32 v[130:131], v[128:129], v[126:127]
	v_pk_mul_f32 v[128:129], v[156:157], v[124:125]
	v_pk_mul_f32 v[124:125], v[148:149], v[134:135] op_sel_hi:[0,1]
	v_pk_mul_f32 v[156:157], v[148:149], v[132:133] op_sel_hi:[0,1]
	v_pk_mul_f32 v[126:127], v[124:125], v[122:123]
	v_pk_mul_f32 v[124:125], v[156:157], v[120:121]
	v_pk_mul_f32 v[120:121], v[142:143], v[134:135] op_sel_hi:[0,1]
	v_pk_mul_f32 v[156:157], v[142:143], v[132:133] op_sel_hi:[0,1]
	v_pk_mul_f32 v[122:123], v[120:121], v[118:119]
	v_pk_mul_f32 v[120:121], v[156:157], v[116:117]
	v_pk_mul_f32 v[116:117], v[150:151], v[134:135] op_sel_hi:[0,1]
	v_pk_mul_f32 v[156:157], v[150:151], v[132:133] op_sel_hi:[0,1]
	v_pk_mul_f32 v[118:119], v[116:117], v[114:115]
	v_pk_mul_f32 v[116:117], v[156:157], v[112:113]
	v_pk_mul_f32 v[112:113], v[138:139], v[134:135] op_sel_hi:[0,1]
	v_pk_mul_f32 v[156:157], v[138:139], v[132:133] op_sel_hi:[0,1]
	v_pk_mul_f32 v[114:115], v[112:113], v[110:111]
	v_pk_mul_f32 v[112:113], v[156:157], v[108:109]
	v_pk_mul_f32 v[108:109], v[152:153], v[134:135] op_sel_hi:[0,1]
	v_pk_mul_f32 v[156:157], v[152:153], v[132:133] op_sel_hi:[0,1]
	v_pk_mul_f32 v[110:111], v[108:109], v[106:107]
	v_pk_mul_f32 v[108:109], v[156:157], v[104:105]
	v_pk_mul_f32 v[104:105], v[136:137], v[134:135] op_sel_hi:[0,1]
	v_pk_mul_f32 v[106:107], v[136:137], v[132:133] op_sel_hi:[0,1]
	v_pk_mul_f32 v[102:103], v[104:105], v[102:103]
	v_pk_mul_f32 v[104:105], v[146:147], v[134:135] op_sel_hi:[0,1]
	v_pk_mul_f32 v[132:133], v[146:147], v[132:133] op_sel_hi:[0,1]
	v_pk_mul_f32 v[100:101], v[106:107], v[100:101]
	v_pk_mul_f32 v[106:107], v[104:105], v[78:79]
	v_pk_mul_f32 v[104:105], v[132:133], v[76:77]
	s_nop 0
	ds_read_b128 v[132:135], v230 offset:528
	v_cvt_f32_i32_e32 v69, v69
	v_cvt_f32_i32_e32 v68, v68
	v_cvt_f32_i32_e32 v71, v71
	v_cvt_f32_i32_e32 v70, v70
	v_cvt_f32_i32_e32 v61, v61
	v_cvt_f32_i32_e32 v60, v60
	v_cvt_f32_i32_e32 v63, v63
	v_cvt_f32_i32_e32 v62, v62
	v_cvt_f32_i32_e32 v45, v45
	v_cvt_f32_i32_e32 v44, v44
	v_cvt_f32_i32_e32 v47, v47
	v_cvt_f32_i32_e32 v46, v46
	v_cvt_f32_i32_e32 v41, v41
	v_cvt_f32_i32_e32 v40, v40
	v_cvt_f32_i32_e32 v43, v43
	v_cvt_f32_i32_e32 v42, v42
	v_cvt_f32_i32_e32 v33, v33
	v_cvt_f32_i32_e32 v32, v32
	v_cvt_f32_i32_e32 v35, v35
	v_cvt_f32_i32_e32 v34, v34
	v_cvt_f32_i32_e32 v37, v37
	v_cvt_f32_i32_e32 v36, v36
	v_cvt_f32_i32_e32 v39, v39
	v_cvt_f32_i32_e32 v38, v38
	s_waitcnt lgkmcnt(0)
	v_pk_mul_f32 v[76:77], v[144:145], v[134:135] op_sel_hi:[0,1]
	v_pk_mul_f32 v[144:145], v[144:145], v[132:133] op_sel_hi:[0,1]
	v_pk_mul_f32 v[78:79], v[76:77], v[70:71]
	v_pk_mul_f32 v[76:77], v[144:145], v[68:69]
	v_cvt_f32_i32_e32 v69, v73
	v_cvt_f32_i32_e32 v68, v72
	v_cvt_f32_i32_e32 v71, v75
	v_cvt_f32_i32_e32 v70, v74
	v_pk_mul_f32 v[72:73], v[148:149], v[134:135] op_sel_hi:[0,1]
	v_pk_mul_f32 v[144:145], v[148:149], v[132:133] op_sel_hi:[0,1]
	v_pk_mul_f32 v[74:75], v[72:73], v[70:71]
	v_pk_mul_f32 v[72:73], v[144:145], v[68:69]
	v_cvt_f32_i32_e32 v69, v81
	v_cvt_f32_i32_e32 v68, v80
	v_cvt_f32_i32_e32 v71, v83
	v_cvt_f32_i32_e32 v70, v82
	v_pk_mul_f32 v[80:81], v[142:143], v[134:135] op_sel_hi:[0,1]
	v_pk_mul_f32 v[82:83], v[142:143], v[132:133] op_sel_hi:[0,1]
	v_pk_mul_f32 v[68:69], v[82:83], v[68:69]
	v_pk_mul_f32 v[70:71], v[80:81], v[70:71]
	v_pk_mul_f32 v[80:81], v[150:151], v[134:135] op_sel_hi:[0,1]
	v_pk_mul_f32 v[82:83], v[150:151], v[132:133] op_sel_hi:[0,1]
	v_pk_mul_f32 v[62:63], v[80:81], v[62:63]
	v_pk_mul_f32 v[60:61], v[82:83], v[60:61]
	v_pk_mul_f32 v[80:81], v[138:139], v[134:135] op_sel_hi:[0,1]
	v_pk_mul_f32 v[82:83], v[138:139], v[132:133] op_sel_hi:[0,1]
	v_pk_mul_f32 v[46:47], v[80:81], v[46:47]
	v_pk_mul_f32 v[44:45], v[82:83], v[44:45]
	v_pk_mul_f32 v[80:81], v[152:153], v[134:135] op_sel_hi:[0,1]
	v_pk_mul_f32 v[82:83], v[152:153], v[132:133] op_sel_hi:[0,1]
	v_pk_mul_f32 v[42:43], v[80:81], v[42:43]
	v_pk_mul_f32 v[40:41], v[82:83], v[40:41]
	v_pk_mul_f32 v[80:81], v[136:137], v[134:135] op_sel_hi:[0,1]
	v_pk_mul_f32 v[82:83], v[136:137], v[132:133] op_sel_hi:[0,1]
	v_pk_mul_f32 v[34:35], v[80:81], v[34:35]
	v_pk_mul_f32 v[32:33], v[82:83], v[32:33]
	v_pk_mul_f32 v[80:81], v[146:147], v[134:135] op_sel_hi:[0,1]
	v_pk_mul_f32 v[82:83], v[146:147], v[132:133] op_sel_hi:[0,1]
	v_pk_mul_f32 v[38:39], v[80:81], v[38:39]
	v_pk_mul_f32 v[36:37], v[82:83], v[36:37]
	s_nop 0
	v_cmp_gt_i32_e32 vcc, s94, v149
	s_and_saveexec_b64 s[6:7], vcc
	s_cbranch_execz .LBB0_809
	s_movk_i32 s5, 0x80
	v_cmp_gt_i32_e32 vcc, s5, v149
	s_add_i32 s5, s4, 0x2a80
	v_mov_b32_e32 v80, s5
	v_mov_b32_e32 v81, s4
	v_cndmask_b32_e32 v80, v80, v81, vcc
	v_add_u32_e32 v80, v80, v149
	v_ashrrev_i32_e32 v81, 31, v80
	v_readlane_b32 s8, v251, 21
	v_lshlrev_b64 v[80:81], 2, v[80:81]
	v_readlane_b32 s22, v251, 35
	v_readlane_b32 s23, v251, 36
	v_lshl_add_u32 v132, v149, 2, 0
	v_readlane_b32 s9, v251, 22
	v_lshl_add_u64 v[82:83], s[22:23], 0, v[80:81]
	v_readlane_b32 s10, v251, 23
	v_readlane_b32 s11, v251, 24
	v_readlane_b32 s12, v251, 25
	v_readlane_b32 s13, v251, 26
	v_readlane_b32 s14, v251, 27
	v_readlane_b32 s15, v251, 28
	v_readlane_b32 s16, v251, 29
	v_readlane_b32 s17, v251, 30
	v_readlane_b32 s18, v251, 31
	v_readlane_b32 s19, v251, 32
	v_readlane_b32 s20, v251, 33
	v_readlane_b32 s21, v251, 34
	v_add_u32_e32 v135, 0x20000, v132
	v_add_co_u32_e32 v132, vcc, 0x15000, v82
	v_readlane_b32 s8, v251, 5
	s_nop 0
	v_addc_co_u32_e32 v133, vcc, 0, v83, vcc
	global_load_dword v134, v[82:83], off
	v_readlane_b32 s9, v251, 6
	global_load_dword v132, v[132:133], off offset:2048
	v_add_co_u32_e32 v82, vcc, 0x2b000, v82
	v_lshl_add_u64 v[80:81], s[8:9], 0, v[80:81]
	s_nop 0
	v_addc_co_u32_e32 v83, vcc, 0, v83, vcc
	global_load_dword v82, v[82:83], off
	v_readlane_b32 s10, v251, 7
	global_load_dword v80, v[80:81], off
	v_readlane_b32 s11, v251, 8
	v_readlane_b32 s12, v251, 9
	v_readlane_b32 s13, v251, 10
	v_readlane_b32 s14, v251, 11
	v_readlane_b32 s15, v251, 12
	v_readlane_b32 s16, v251, 13
	v_readlane_b32 s17, v251, 14
	v_readlane_b32 s18, v251, 15
	v_readlane_b32 s19, v251, 16
	v_readlane_b32 s20, v251, 17
	v_readlane_b32 s21, v251, 18
	v_readlane_b32 s22, v251, 19
	v_readlane_b32 s23, v251, 20
	s_waitcnt vmcnt(2)
	ds_write2st64_b32 v135, v134, v132 offset1:4
	s_waitcnt vmcnt(0)
	ds_write2st64_b32 v135, v82, v80 offset0:8 offset1:12

	.amdhsa_kernel _Z6mk_fwd4Args
		.amdhsa_group_segment_fixed_size 0
		.amdhsa_private_segment_fixed_size 0
		.amdhsa_kernarg_size 456
		.amdhsa_user_sgpr_count 2
		.amdhsa_user_sgpr_dispatch_ptr 0
		.amdhsa_user_sgpr_queue_ptr 0
		.amdhsa_user_sgpr_kernarg_segment_ptr 1
		.amdhsa_user_sgpr_dispatch_id 0
		.amdhsa_user_sgpr_kernarg_preload_length 0
		.amdhsa_user_sgpr_kernarg_preload_offset 0
		.amdhsa_user_sgpr_private_segment_size 0
		.amdhsa_uses_dynamic_stack 0
		.amdhsa_enable_private_segment 0
		.amdhsa_system_sgpr_workgroup_id_x 1
		.amdhsa_system_sgpr_workgroup_id_y 0
		.amdhsa_system_sgpr_workgroup_id_z 0
		.amdhsa_system_sgpr_workgroup_info 0
		.amdhsa_system_vgpr_workitem_id 0
		.amdhsa_next_free_vgpr 256
		.amdhsa_next_free_sgpr 102
		.amdhsa_accum_offset 256
		.amdhsa_reserve_vcc 1
		.amdhsa_float_round_mode_32 0
		.amdhsa_float_round_mode_16_64 0
		.amdhsa_float_denorm_mode_32 3
		.amdhsa_float_denorm_mode_16_64 3
		.amdhsa_dx10_clamp 1
		.amdhsa_ieee_mode 1
		.amdhsa_fp16_overflow 0
		.amdhsa_tg_split 0
		.amdhsa_exception_fp_ieee_invalid_op 0
		.amdhsa_exception_fp_denorm_src 0
		.amdhsa_exception_fp_ieee_div_zero 0
		.amdhsa_exception_fp_ieee_overflow 0
		.amdhsa_exception_fp_ieee_underflow 0
		.amdhsa_exception_fp_ieee_inexact 0
		.amdhsa_exception_int_div_zero 0
	.end_amdhsa_kernel

amdhsa.kernels:
  - .agpr_count:     0
    .args:
      - .offset:         0
        .size:           200
        .value_kind:     by_value
      - .offset:         200
        .size:           4
        .value_kind:     hidden_block_count_x
      - .offset:         204
        .size:           4
        .value_kind:     hidden_block_count_y
      - .offset:         208
        .size:           4
        .value_kind:     hidden_block_count_z
      - .offset:         212
        .size:           2
        .value_kind:     hidden_group_size_x
      - .offset:         214
        .size:           2
        .value_kind:     hidden_group_size_y
      - .offset:         216
        .size:           2
        .value_kind:     hidden_group_size_z
      - .offset:         218
        .size:           2
        .value_kind:     hidden_remainder_x
      - .offset:         220
        .size:           2
        .value_kind:     hidden_remainder_y
      - .offset:         222
        .size:           2
        .value_kind:     hidden_remainder_z
      - .offset:         240
        .size:           8
        .value_kind:     hidden_global_offset_x
      - .offset:         248
        .size:           8
        .value_kind:     hidden_global_offset_y
      - .offset:         256
        .size:           8
        .value_kind:     hidden_global_offset_z
      - .offset:         264
        .size:           2
        .value_kind:     hidden_grid_dims
      - .offset:         320
        .size:           4
        .value_kind:     hidden_dynamic_lds_size
    .group_segment_fixed_size: 0
    .kernarg_segment_align: 8
    .kernarg_segment_size: 456
    .language:       OpenCL C
    .language_version:
      - 2
      - 0
    .max_flat_workgroup_size: 512
    .name:           _Z6mk_fwd4Args
    .private_segment_fixed_size: 0
    .sgpr_count:     108
    .sgpr_spill_count: 118
    .symbol:         _Z6mk_fwd4Args.kd
    .uniform_work_group_size: 1
    .uses_dynamic_stack: false
    .vgpr_count:     256
    .vgpr_spill_count: 0
    .wavefront_size: 64
